# stack12 + grid barrier: L1 invalidate (buffer_inv sc1) issued at arrival (before polling / right behind the top-level arrive atomic) instead of after the release, so its ~1.5us completion is off the r
# speedup vs baseline: 1.0021x; 1.0021x over previous
; __device__ __forceinline__ unsigned xb_ld(unsigned* p)              { return __hip_atomic_load(p, __ATOMIC_RELAXED, __HIP_MEMORY_SCOPE_AGENT); }
; __device__ __forceinline__ unsigned xb_add(unsigned* p, unsigned v) { return __hip_atomic_fetch_add(p, v, __ATOMIC_RELAXED, __HIP_MEMORY_SCOPE_AGENT); }
; #define XB_SPIN(cond, bar) do { unsigned _sp = 0; while (cond) { __builtin_amdgcn_s_sleep(1); \
;     if ((++_sp & 255u) == 0u) { if (xb_ld(&(bar)[XB_TMO])) break; if (_sp > XB_SPIN_CAP) { atomicAdd(&(bar)[XB_TMO], 1u); break; } } } } while (0)
; __device__ __forceinline__ void xcd_barrier(const XcdBarrier& b) {
;     ...
;         const unsigned old = xb_add(&bar[XB_XSUB(bx)], 1u);
;         const unsigned gen = old / nloc;
;         if (old + 1u == (gen + 1u) * nloc) {
;             __builtin_amdgcn_fence(__ATOMIC_RELEASE, "agent");
;             asm volatile("s_waitcnt vmcnt(0)" ::: "memory");
;             const unsigned og = xb_add(&bar[XB_TOP], 1u);
;             const unsigned tg = og / nx;
;             if (og + 1u == (tg + 1u) * nx) xb_add(&bar[XB_TOPGEN], 1u);
;             else XB_SPIN(xb_ld(&bar[XB_TOPGEN]) == tg, bar);
;             __builtin_amdgcn_fence(__ATOMIC_ACQUIRE, "agent");
;             asm volatile("s_waitcnt vmcnt(0)" ::: "memory");
;         } else {
;             XB_SPIN(xb_ld(&bar[XB_TOPGEN]) == gen, bar);
;             __builtin_amdgcn_fence(__ATOMIC_ACQUIRE, "agent");
;             asm volatile("s_waitcnt vmcnt(0)" ::: "memory");
.LBB0_225:
	s_lshl_b32 s1, s1, 6
	s_add_i32 s92, s1, 0x500
	s_lshl_b64 s[6:7], s[92:93], 2
	s_add_u32 s6, s52, s6
	s_addc_u32 s7, s53, s7
	v_mov_b64_e32 v[4:5], s[6:7]
	v_mov_b32_e32 v3, 1
	flat_atomic_add v4, v[4:5], v3 sc0
	v_cvt_f32_u32_e32 v3, v2
	v_sub_u32_e32 v5, 0, v2
	v_rcp_iflag_f32_e32 v3, v3
	s_nop 0
	v_mul_f32_e32 v3, 0x4f7ffffe, v3
	v_cvt_u32_f32_e32 v3, v3
	v_mul_lo_u32 v5, v5, v3
	v_mul_hi_u32 v5, v3, v5
	v_add_u32_e32 v3, v3, v5
	s_waitcnt vmcnt(0) lgkmcnt(0)
	v_mul_hi_u32 v3, v4, v3
	v_mul_lo_u32 v5, v3, v2
	v_sub_u32_e32 v5, v4, v5
	v_cmp_ge_u32_e32 vcc, v5, v2
	v_add_u32_e32 v6, 1, v3
	s_nop 0
	v_cndmask_b32_e32 v3, v3, v6, vcc
	v_sub_u32_e32 v6, v5, v2
	v_cndmask_b32_e32 v5, v5, v6, vcc
	v_cmp_ge_u32_e32 vcc, v5, v2
	v_add_u32_e32 v5, 1, v3
	v_add_u32_e32 v6, 1, v4
	v_cndmask_b32_e32 v3, v3, v5, vcc
	v_mad_u64_u32 v[4:5], s[6:7], v2, v3, v[2:3]
	v_cmp_ne_u32_e32 vcc, v6, v4
	s_and_saveexec_b64 s[6:7], vcc
	s_xor_b64 s[6:7], exec, s[6:7]
	s_cbranch_execz .LBB0_238
	buffer_inv sc1
	v_mov_b32_e32 v0, s52
	v_add_co_u32_e32 v4, vcc, 0x3000, v0
	v_mov_b32_e32 v0, s53
	s_nop 0
	v_addc_co_u32_e32 v5, vcc, 0, v0, vcc
	flat_load_dword v0, v[4:5] offset:1280 sc1
	s_add_u32 s10, s52, 0x3500
	s_addc_u32 s11, s53, 0
	s_waitcnt vmcnt(0) lgkmcnt(0)
	v_cmp_eq_u32_e32 vcc, v0, v3
	s_and_saveexec_b64 s[8:9], vcc
	s_cbranch_execz .LBB0_237
	s_mov_b32 s1, 1
	s_mov_b64 s[12:13], 0
	s_branch .LBB0_229

; __device__ __forceinline__ unsigned xb_ld(unsigned* p)              { return __hip_atomic_load(p, __ATOMIC_RELAXED, __HIP_MEMORY_SCOPE_AGENT); }
; __device__ __forceinline__ unsigned xb_add(unsigned* p, unsigned v) { return __hip_atomic_fetch_add(p, v, __ATOMIC_RELAXED, __HIP_MEMORY_SCOPE_AGENT); }
; #define XB_SPIN(cond, bar) do { unsigned _sp = 0; while (cond) { __builtin_amdgcn_s_sleep(1); \
;     if ((++_sp & 255u) == 0u) { if (xb_ld(&(bar)[XB_TMO])) break; if (_sp > XB_SPIN_CAP) { atomicAdd(&(bar)[XB_TMO], 1u); break; } } } } while (0)
; __device__ __forceinline__ void xcd_barrier(const XcdBarrier& b) {
;     ...
;         if (old + 1u == (gen + 1u) * nloc) {
;             __builtin_amdgcn_fence(__ATOMIC_RELEASE, "agent");
;             asm volatile("s_waitcnt vmcnt(0)" ::: "memory");
;             const unsigned og = xb_add(&bar[XB_TOP], 1u);
;             const unsigned tg = og / nx;
;             if (og + 1u == (tg + 1u) * nx) xb_add(&bar[XB_TOPGEN], 1u);
;             else XB_SPIN(xb_ld(&bar[XB_TOPGEN]) == tg, bar);
;             __builtin_amdgcn_fence(__ATOMIC_ACQUIRE, "agent");
;             asm volatile("s_waitcnt vmcnt(0)" ::: "memory");
.LBB0_238:
	s_andn2_saveexec_b64 s[6:7], s[6:7]
	s_cbranch_execz .LBB0_254
	v_mov_b32_e32 v2, s52
	v_add_co_u32_e32 v2, vcc, 0x3000, v2
	v_mov_b32_e32 v3, s53
	buffer_wbl2 sc1
	s_waitcnt vmcnt(0)
	v_addc_co_u32_e32 v3, vcc, 0, v3, vcc
	v_mov_b32_e32 v4, 1
	flat_atomic_add v2, v[2:3], v4 offset:1024 sc0
	buffer_inv sc1
	v_cvt_f32_u32_e32 v3, v0
	v_sub_u32_e32 v4, 0, v0
	s_mov_b64 s[10:11], -1
	v_rcp_iflag_f32_e32 v3, v3
	s_nop 0
	v_mul_f32_e32 v3, 0x4f7ffffe, v3
	v_cvt_u32_f32_e32 v3, v3
	v_mul_lo_u32 v4, v4, v3
	v_mul_hi_u32 v4, v3, v4
	v_add_u32_e32 v3, v3, v4
	s_waitcnt vmcnt(1) lgkmcnt(0)
	v_mul_hi_u32 v3, v2, v3
	v_mul_lo_u32 v4, v3, v0
	v_sub_u32_e32 v4, v2, v4
	v_cmp_ge_u32_e32 vcc, v4, v0
	v_add_u32_e32 v5, 1, v3
	s_nop 0
	v_cndmask_b32_e32 v3, v3, v5, vcc
	v_sub_u32_e32 v5, v4, v0
	v_cndmask_b32_e32 v4, v4, v5, vcc
	v_cmp_ge_u32_e32 vcc, v4, v0
	v_add_u32_e32 v4, 1, v3
	v_add_u32_e32 v5, 1, v2
	v_cndmask_b32_e32 v4, v3, v4, vcc
	v_mad_u64_u32 v[2:3], s[6:7], v0, v4, v[0:1]
	s_add_u32 s6, s52, 0x3500
	s_addc_u32 s7, s53, 0
	v_cmp_ne_u32_e32 vcc, v5, v2
	v_mov_b64_e32 v[2:3], s[6:7]
	s_and_saveexec_b64 s[8:9], vcc
	s_cbranch_execz .LBB0_251
	v_mov_b64_e32 v[2:3], s[6:7]
	flat_load_dword v0, v[2:3] sc1
	s_mov_b64 s[14:15], 0
	s_waitcnt vmcnt(0) lgkmcnt(0)
	v_cmp_eq_u32_e32 vcc, v0, v4
	s_and_saveexec_b64 s[12:13], vcc
	s_cbranch_execz .LBB0_250
	s_add_u32 s10, s52, 0x200
	s_addc_u32 s11, s53, 0
	s_mov_b32 s1, 1
	s_branch .LBB0_243

; __device__ __forceinline__ unsigned xb_ld(unsigned* p)              { return __hip_atomic_load(p, __ATOMIC_RELAXED, __HIP_MEMORY_SCOPE_AGENT); }
; #define XB_SPIN(cond, bar) do { unsigned _sp = 0; while (cond) { __builtin_amdgcn_s_sleep(1); \
;     if ((++_sp & 255u) == 0u) { if (xb_ld(&(bar)[XB_TMO])) break; if (_sp > XB_SPIN_CAP) { atomicAdd(&(bar)[XB_TMO], 1u); break; } } } } while (0)
; __device__ __forceinline__ void xcd_barrier(const XcdBarrier& b) {
;     ...
;             else XB_SPIN(xb_ld(&bar[XB_TOPGEN]) == tg, bar);
;             __builtin_amdgcn_fence(__ATOMIC_ACQUIRE, "agent");
;             asm volatile("s_waitcnt vmcnt(0)" ::: "memory");
.LBB0_253:
	s_or_b64 exec, exec, s[6:7]
	s_waitcnt vmcnt(0) lgkmcnt(0)
.LBB0_254:
	s_or_b64 exec, exec, s[38:39]

; __device__ __forceinline__ unsigned xb_ld(unsigned* p)              { return __hip_atomic_load(p, __ATOMIC_RELAXED, __HIP_MEMORY_SCOPE_AGENT); }
; #define XB_SPIN(cond, bar) do { unsigned _sp = 0; while (cond) { __builtin_amdgcn_s_sleep(1); \
;     if ((++_sp & 255u) == 0u) { if (xb_ld(&(bar)[XB_TMO])) break; if (_sp > XB_SPIN_CAP) { atomicAdd(&(bar)[XB_TMO], 1u); break; } } } } while (0)
; __device__ __forceinline__ void xcd_barrier(const XcdBarrier& b) {
;     ...
;             else XB_SPIN(xb_ld(&bar[XB_TOPGEN]) == tg, bar);
;             __builtin_amdgcn_fence(__ATOMIC_ACQUIRE, "agent");
;             asm volatile("s_waitcnt vmcnt(0)" ::: "memory");
.LBB0_330:
	s_or_b64 exec, exec, s[6:7]
	s_waitcnt vmcnt(0) lgkmcnt(0)
.LBB0_331:
	s_or_b64 exec, exec, s[38:39]

; __device__ __forceinline__ unsigned xb_ld(unsigned* p)              { return __hip_atomic_load(p, __ATOMIC_RELAXED, __HIP_MEMORY_SCOPE_AGENT); }
; #define XB_SPIN(cond, bar) do { unsigned _sp = 0; while (cond) { __builtin_amdgcn_s_sleep(1); \
;     if ((++_sp & 255u) == 0u) { if (xb_ld(&(bar)[XB_TMO])) break; if (_sp > XB_SPIN_CAP) { atomicAdd(&(bar)[XB_TMO], 1u); break; } } } } while (0)
; __device__ __forceinline__ void xcd_barrier(const XcdBarrier& b) {
;     ...
;             else XB_SPIN(xb_ld(&bar[XB_TOPGEN]) == tg, bar);
;             __builtin_amdgcn_fence(__ATOMIC_ACQUIRE, "agent");
;             asm volatile("s_waitcnt vmcnt(0)" ::: "memory");
.LBB0_491:
	s_or_b64 exec, exec, s[6:7]
	s_waitcnt vmcnt(0) lgkmcnt(0)
.LBB0_492:
	s_or_b64 exec, exec, s[38:39]

; __device__ __forceinline__ unsigned xb_ld(unsigned* p)              { return __hip_atomic_load(p, __ATOMIC_RELAXED, __HIP_MEMORY_SCOPE_AGENT); }
; #define XB_SPIN(cond, bar) do { unsigned _sp = 0; while (cond) { __builtin_amdgcn_s_sleep(1); \
;     if ((++_sp & 255u) == 0u) { if (xb_ld(&(bar)[XB_TMO])) break; if (_sp > XB_SPIN_CAP) { atomicAdd(&(bar)[XB_TMO], 1u); break; } } } } while (0)
; __device__ __forceinline__ void xcd_barrier(const XcdBarrier& b) {
;     ...
;             else XB_SPIN(xb_ld(&bar[XB_TOPGEN]) == tg, bar);
;             __builtin_amdgcn_fence(__ATOMIC_ACQUIRE, "agent");
;             asm volatile("s_waitcnt vmcnt(0)" ::: "memory");
.LBB0_625:
	s_or_b64 exec, exec, s[6:7]
	s_waitcnt vmcnt(0) lgkmcnt(0)
.LBB0_626:
	s_or_b64 exec, exec, s[38:39]

; __device__ __forceinline__ unsigned xb_ld(unsigned* p)              { return __hip_atomic_load(p, __ATOMIC_RELAXED, __HIP_MEMORY_SCOPE_AGENT); }
; #define XB_SPIN(cond, bar) do { unsigned _sp = 0; while (cond) { __builtin_amdgcn_s_sleep(1); \
;     if ((++_sp & 255u) == 0u) { if (xb_ld(&(bar)[XB_TMO])) break; if (_sp > XB_SPIN_CAP) { atomicAdd(&(bar)[XB_TMO], 1u); break; } } } } while (0)
; __device__ __forceinline__ void xcd_barrier(const XcdBarrier& b) {
;     ...
;             else XB_SPIN(xb_ld(&bar[XB_TOPGEN]) == tg, bar);
;             __builtin_amdgcn_fence(__ATOMIC_ACQUIRE, "agent");
;             asm volatile("s_waitcnt vmcnt(0)" ::: "memory");
.LBB0_759:
	s_or_b64 exec, exec, s[6:7]
	s_waitcnt vmcnt(0) lgkmcnt(0)
.LBB0_760:
	s_or_b64 exec, exec, s[38:39]

; __device__ __forceinline__ unsigned xb_ld(unsigned* p)              { return __hip_atomic_load(p, __ATOMIC_RELAXED, __HIP_MEMORY_SCOPE_AGENT); }
; #define XB_SPIN(cond, bar) do { unsigned _sp = 0; while (cond) { __builtin_amdgcn_s_sleep(1); \
;     if ((++_sp & 255u) == 0u) { if (xb_ld(&(bar)[XB_TMO])) break; if (_sp > XB_SPIN_CAP) { atomicAdd(&(bar)[XB_TMO], 1u); break; } } } } while (0)
; __device__ __forceinline__ void xcd_barrier(const XcdBarrier& b) {
;     ...
;             else XB_SPIN(xb_ld(&bar[XB_TOPGEN]) == tg, bar);
;             __builtin_amdgcn_fence(__ATOMIC_ACQUIRE, "agent");
;             asm volatile("s_waitcnt vmcnt(0)" ::: "memory");
.LBB0_823:
	s_or_b64 exec, exec, s[6:7]
	s_waitcnt vmcnt(0) lgkmcnt(0)
.LBB0_824:
	s_or_b64 exec, exec, s[38:39]

; __device__ __forceinline__ unsigned xb_ld(unsigned* p)              { return __hip_atomic_load(p, __ATOMIC_RELAXED, __HIP_MEMORY_SCOPE_AGENT); }
; #define XB_SPIN(cond, bar) do { unsigned _sp = 0; while (cond) { __builtin_amdgcn_s_sleep(1); \
;     if ((++_sp & 255u) == 0u) { if (xb_ld(&(bar)[XB_TMO])) break; if (_sp > XB_SPIN_CAP) { atomicAdd(&(bar)[XB_TMO], 1u); break; } } } } while (0)
; __device__ __forceinline__ void xcd_barrier(const XcdBarrier& b) {
;     ...
;             else XB_SPIN(xb_ld(&bar[XB_TOPGEN]) == tg, bar);
;             __builtin_amdgcn_fence(__ATOMIC_ACQUIRE, "agent");
;             asm volatile("s_waitcnt vmcnt(0)" ::: "memory");
.LBB0_937:
	s_or_b64 exec, exec, s[6:7]
	s_waitcnt vmcnt(0) lgkmcnt(0)
.LBB0_938:
	s_or_b64 exec, exec, s[38:39]

; __device__ __forceinline__ unsigned xb_ld(unsigned* p)              { return __hip_atomic_load(p, __ATOMIC_RELAXED, __HIP_MEMORY_SCOPE_AGENT); }
; #define XB_SPIN(cond, bar) do { unsigned _sp = 0; while (cond) { __builtin_amdgcn_s_sleep(1); \
;     if ((++_sp & 255u) == 0u) { if (xb_ld(&(bar)[XB_TMO])) break; if (_sp > XB_SPIN_CAP) { atomicAdd(&(bar)[XB_TMO], 1u); break; } } } } while (0)
; __device__ __forceinline__ void xcd_barrier(const XcdBarrier& b) {
;     ...
;             else XB_SPIN(xb_ld(&bar[XB_TOPGEN]) == tg, bar);
;             __builtin_amdgcn_fence(__ATOMIC_ACQUIRE, "agent");
;             asm volatile("s_waitcnt vmcnt(0)" ::: "memory");
.LBB0_991:
	s_or_b64 exec, exec, s[6:7]
	s_waitcnt vmcnt(0) lgkmcnt(0)
.LBB0_992:
	s_or_b64 exec, exec, s[38:39]

; __device__ __forceinline__ unsigned xb_ld(unsigned* p)              { return __hip_atomic_load(p, __ATOMIC_RELAXED, __HIP_MEMORY_SCOPE_AGENT); }
; __device__ __forceinline__ unsigned xb_add(unsigned* p, unsigned v) { return __hip_atomic_fetch_add(p, v, __ATOMIC_RELAXED, __HIP_MEMORY_SCOPE_AGENT); }
; #define XB_SPIN(cond, bar) do { unsigned _sp = 0; while (cond) { __builtin_amdgcn_s_sleep(1); \
;     if ((++_sp & 255u) == 0u) { if (xb_ld(&(bar)[XB_TMO])) break; if (_sp > XB_SPIN_CAP) { atomicAdd(&(bar)[XB_TMO], 1u); break; } } } } while (0)
; __device__ __forceinline__ void xcd_barrier(const XcdBarrier& b) {
;     ...
;         const unsigned old = xb_add(&bar[XB_XSUB(bx)], 1u);
;         const unsigned gen = old / nloc;
;         if (old + 1u == (gen + 1u) * nloc) {
;             __builtin_amdgcn_fence(__ATOMIC_RELEASE, "agent");
;             asm volatile("s_waitcnt vmcnt(0)" ::: "memory");
;             const unsigned og = xb_add(&bar[XB_TOP], 1u);
;             const unsigned tg = og / nx;
;             if (og + 1u == (tg + 1u) * nx) xb_add(&bar[XB_TOPGEN], 1u);
;             else XB_SPIN(xb_ld(&bar[XB_TOPGEN]) == tg, bar);
;             __builtin_amdgcn_fence(__ATOMIC_ACQUIRE, "agent");
;             asm volatile("s_waitcnt vmcnt(0)" ::: "memory");
;         } else {
;             XB_SPIN(xb_ld(&bar[XB_TOPGEN]) == gen, bar);
;             __builtin_amdgcn_fence(__ATOMIC_ACQUIRE, "agent");
;             asm volatile("s_waitcnt vmcnt(0)" ::: "memory");
.LBB0_1050:
	s_lshl_b32 s1, s1, 6
	s_add_i32 s92, s1, 0x500
	s_lshl_b64 s[8:9], s[92:93], 2
	s_add_u32 s8, s64, s8
	s_addc_u32 s9, s65, s9
	v_mov_b64_e32 v[4:5], s[8:9]
	v_mov_b32_e32 v3, 1
	flat_atomic_add v4, v[4:5], v3 sc0
	v_cvt_f32_u32_e32 v3, v2
	v_sub_u32_e32 v5, 0, v2
	v_rcp_iflag_f32_e32 v3, v3
	s_nop 0
	v_mul_f32_e32 v3, 0x4f7ffffe, v3
	v_cvt_u32_f32_e32 v3, v3
	v_mul_lo_u32 v5, v5, v3
	v_mul_hi_u32 v5, v3, v5
	v_add_u32_e32 v3, v3, v5
	s_waitcnt vmcnt(0) lgkmcnt(0)
	v_mul_hi_u32 v3, v4, v3
	v_mul_lo_u32 v5, v3, v2
	v_sub_u32_e32 v5, v4, v5
	v_cmp_ge_u32_e32 vcc, v5, v2
	v_add_u32_e32 v6, 1, v3
	s_nop 0
	v_cndmask_b32_e32 v3, v3, v6, vcc
	v_sub_u32_e32 v6, v5, v2
	v_cndmask_b32_e32 v5, v5, v6, vcc
	v_cmp_ge_u32_e32 vcc, v5, v2
	v_add_u32_e32 v5, 1, v3
	v_add_u32_e32 v6, 1, v4
	v_cndmask_b32_e32 v3, v3, v5, vcc
	v_mad_u64_u32 v[4:5], s[8:9], v2, v3, v[2:3]
	v_cmp_ne_u32_e32 vcc, v6, v4
	s_and_saveexec_b64 s[8:9], vcc
	s_xor_b64 s[8:9], exec, s[8:9]
	s_cbranch_execz .LBB0_1063
	buffer_inv sc1
	v_mov_b32_e32 v0, s64
	v_add_co_u32_e32 v4, vcc, 0x3000, v0
	v_mov_b32_e32 v0, s65
	s_nop 0
	v_addc_co_u32_e32 v5, vcc, 0, v0, vcc
	flat_load_dword v0, v[4:5] offset:1280 sc1
	s_add_u32 s12, s64, 0x3500
	s_addc_u32 s13, s65, 0
	s_waitcnt vmcnt(0) lgkmcnt(0)
	v_cmp_eq_u32_e32 vcc, v0, v3
	s_and_saveexec_b64 s[10:11], vcc
	s_cbranch_execz .LBB0_1062
	s_mov_b32 s1, 1
	s_mov_b64 s[14:15], 0
	s_branch .LBB0_1054

; __device__ __forceinline__ unsigned xb_ld(unsigned* p)              { return __hip_atomic_load(p, __ATOMIC_RELAXED, __HIP_MEMORY_SCOPE_AGENT); }
; __device__ __forceinline__ unsigned xb_add(unsigned* p, unsigned v) { return __hip_atomic_fetch_add(p, v, __ATOMIC_RELAXED, __HIP_MEMORY_SCOPE_AGENT); }
; #define XB_SPIN(cond, bar) do { unsigned _sp = 0; while (cond) { __builtin_amdgcn_s_sleep(1); \
;     if ((++_sp & 255u) == 0u) { if (xb_ld(&(bar)[XB_TMO])) break; if (_sp > XB_SPIN_CAP) { atomicAdd(&(bar)[XB_TMO], 1u); break; } } } } while (0)
; __device__ __forceinline__ void xcd_barrier(const XcdBarrier& b) {
;     ...
;         if (old + 1u == (gen + 1u) * nloc) {
;             __builtin_amdgcn_fence(__ATOMIC_RELEASE, "agent");
;             asm volatile("s_waitcnt vmcnt(0)" ::: "memory");
;             const unsigned og = xb_add(&bar[XB_TOP], 1u);
;             const unsigned tg = og / nx;
;             if (og + 1u == (tg + 1u) * nx) xb_add(&bar[XB_TOPGEN], 1u);
;             else XB_SPIN(xb_ld(&bar[XB_TOPGEN]) == tg, bar);
;             __builtin_amdgcn_fence(__ATOMIC_ACQUIRE, "agent");
;             asm volatile("s_waitcnt vmcnt(0)" ::: "memory");
.LBB0_1063:
	s_andn2_saveexec_b64 s[8:9], s[8:9]
	s_cbranch_execz .LBB0_1079
	v_mov_b32_e32 v2, s64
	v_add_co_u32_e32 v2, vcc, 0x3000, v2
	v_mov_b32_e32 v3, s65
	buffer_wbl2 sc1
	s_waitcnt vmcnt(0)
	v_addc_co_u32_e32 v3, vcc, 0, v3, vcc
	v_mov_b32_e32 v4, 1
	flat_atomic_add v2, v[2:3], v4 offset:1024 sc0
	buffer_inv sc1
	v_cvt_f32_u32_e32 v3, v0
	v_sub_u32_e32 v4, 0, v0
	s_mov_b64 s[12:13], -1
	v_rcp_iflag_f32_e32 v3, v3
	s_nop 0
	v_mul_f32_e32 v3, 0x4f7ffffe, v3
	v_cvt_u32_f32_e32 v3, v3
	v_mul_lo_u32 v4, v4, v3
	v_mul_hi_u32 v4, v3, v4
	v_add_u32_e32 v3, v3, v4
	s_waitcnt vmcnt(1) lgkmcnt(0)
	v_mul_hi_u32 v3, v2, v3
	v_mul_lo_u32 v4, v3, v0
	v_sub_u32_e32 v4, v2, v4
	v_cmp_ge_u32_e32 vcc, v4, v0
	v_add_u32_e32 v5, 1, v3
	s_nop 0
	v_cndmask_b32_e32 v3, v3, v5, vcc
	v_sub_u32_e32 v5, v4, v0
	v_cndmask_b32_e32 v4, v4, v5, vcc
	v_cmp_ge_u32_e32 vcc, v4, v0
	v_add_u32_e32 v4, 1, v3
	v_add_u32_e32 v5, 1, v2
	v_cndmask_b32_e32 v4, v3, v4, vcc
	v_mad_u64_u32 v[2:3], s[8:9], v0, v4, v[0:1]
	s_add_u32 s8, s64, 0x3500
	s_addc_u32 s9, s65, 0
	v_cmp_ne_u32_e32 vcc, v5, v2
	v_mov_b64_e32 v[2:3], s[8:9]
	s_and_saveexec_b64 s[10:11], vcc
	s_cbranch_execz .LBB0_1076
	v_mov_b64_e32 v[2:3], s[8:9]
	flat_load_dword v0, v[2:3] sc1
	s_mov_b64 s[16:17], 0
	s_waitcnt vmcnt(0) lgkmcnt(0)
	v_cmp_eq_u32_e32 vcc, v0, v4
	s_and_saveexec_b64 s[14:15], vcc
	s_cbranch_execz .LBB0_1075
	s_add_u32 s12, s64, 0x200
	s_addc_u32 s13, s65, 0
	s_mov_b32 s1, 1
	s_branch .LBB0_1068

; __device__ __forceinline__ unsigned xb_ld(unsigned* p)              { return __hip_atomic_load(p, __ATOMIC_RELAXED, __HIP_MEMORY_SCOPE_AGENT); }
; #define XB_SPIN(cond, bar) do { unsigned _sp = 0; while (cond) { __builtin_amdgcn_s_sleep(1); \
;     if ((++_sp & 255u) == 0u) { if (xb_ld(&(bar)[XB_TMO])) break; if (_sp > XB_SPIN_CAP) { atomicAdd(&(bar)[XB_TMO], 1u); break; } } } } while (0)
; __device__ __forceinline__ void xcd_barrier(const XcdBarrier& b) {
;     ...
;             else XB_SPIN(xb_ld(&bar[XB_TOPGEN]) == tg, bar);
;             __builtin_amdgcn_fence(__ATOMIC_ACQUIRE, "agent");
;             asm volatile("s_waitcnt vmcnt(0)" ::: "memory");
.LBB0_1078:
	s_or_b64 exec, exec, s[8:9]
	s_waitcnt vmcnt(0) lgkmcnt(0)
.LBB0_1079:
	s_or_b64 exec, exec, s[52:53]

; __device__ __forceinline__ unsigned xb_ld(unsigned* p)              { return __hip_atomic_load(p, __ATOMIC_RELAXED, __HIP_MEMORY_SCOPE_AGENT); }
; #define XB_SPIN(cond, bar) do { unsigned _sp = 0; while (cond) { __builtin_amdgcn_s_sleep(1); \
;     if ((++_sp & 255u) == 0u) { if (xb_ld(&(bar)[XB_TMO])) break; if (_sp > XB_SPIN_CAP) { atomicAdd(&(bar)[XB_TMO], 1u); break; } } } } while (0)
; __device__ __forceinline__ void xcd_barrier(const XcdBarrier& b) {
;     ...
;             else XB_SPIN(xb_ld(&bar[XB_TOPGEN]) == tg, bar);
;             __builtin_amdgcn_fence(__ATOMIC_ACQUIRE, "agent");
;             asm volatile("s_waitcnt vmcnt(0)" ::: "memory");
.LBB0_1138:
	s_or_b64 exec, exec, s[8:9]
	s_waitcnt vmcnt(0) lgkmcnt(0)
.LBB0_1139:
	s_or_b64 exec, exec, s[52:53]

; __device__ __forceinline__ unsigned xb_ld(unsigned* p)              { return __hip_atomic_load(p, __ATOMIC_RELAXED, __HIP_MEMORY_SCOPE_AGENT); }
; #define XB_SPIN(cond, bar) do { unsigned _sp = 0; while (cond) { __builtin_amdgcn_s_sleep(1); \
;     if ((++_sp & 255u) == 0u) { if (xb_ld(&(bar)[XB_TMO])) break; if (_sp > XB_SPIN_CAP) { atomicAdd(&(bar)[XB_TMO], 1u); break; } } } } while (0)
; __device__ __forceinline__ void xcd_barrier(const XcdBarrier& b) {
;     ...
;             else XB_SPIN(xb_ld(&bar[XB_TOPGEN]) == tg, bar);
;             __builtin_amdgcn_fence(__ATOMIC_ACQUIRE, "agent");
;             asm volatile("s_waitcnt vmcnt(0)" ::: "memory");
.LBB0_1205:
	s_or_b64 exec, exec, s[8:9]
	s_waitcnt vmcnt(0) lgkmcnt(0)
.LBB0_1206:
	s_or_b64 exec, exec, s[52:53]

; __device__ __forceinline__ unsigned xb_ld(unsigned* p)              { return __hip_atomic_load(p, __ATOMIC_RELAXED, __HIP_MEMORY_SCOPE_AGENT); }
; __device__ __forceinline__ unsigned xb_add(unsigned* p, unsigned v) { return __hip_atomic_fetch_add(p, v, __ATOMIC_RELAXED, __HIP_MEMORY_SCOPE_AGENT); }
; #define XB_SPIN(cond, bar) do { unsigned _sp = 0; while (cond) { __builtin_amdgcn_s_sleep(1); \
;     if ((++_sp & 255u) == 0u) { if (xb_ld(&(bar)[XB_TMO])) break; if (_sp > XB_SPIN_CAP) { atomicAdd(&(bar)[XB_TMO], 1u); break; } } } } while (0)
; __device__ __forceinline__ void xcd_barrier(const XcdBarrier& b) {
;     ...
;         const unsigned old = xb_add(&bar[XB_XSUB(bx)], 1u);
;         const unsigned gen = old / nloc;
;         if (old + 1u == (gen + 1u) * nloc) {
;             __builtin_amdgcn_fence(__ATOMIC_RELEASE, "agent");
;             asm volatile("s_waitcnt vmcnt(0)" ::: "memory");
;             const unsigned og = xb_add(&bar[XB_TOP], 1u);
;             const unsigned tg = og / nx;
;             if (og + 1u == (tg + 1u) * nx) xb_add(&bar[XB_TOPGEN], 1u);
;             else XB_SPIN(xb_ld(&bar[XB_TOPGEN]) == tg, bar);
;             __builtin_amdgcn_fence(__ATOMIC_ACQUIRE, "agent");
;             asm volatile("s_waitcnt vmcnt(0)" ::: "memory");
;         } else {
;             XB_SPIN(xb_ld(&bar[XB_TOPGEN]) == gen, bar);
;             __builtin_amdgcn_fence(__ATOMIC_ACQUIRE, "agent");
;             asm volatile("s_waitcnt vmcnt(0)" ::: "memory");
.LBB0_1262:
	s_lshl_b32 s0, s0, 6
	s_add_i32 s92, s0, 0x500
	s_lshl_b64 s[0:1], s[92:93], 2
	s_add_u32 s0, s52, s0
	s_addc_u32 s1, s53, s1
	v_mov_b64_e32 v[4:5], s[0:1]
	v_mov_b32_e32 v3, 1
	flat_atomic_add v4, v[4:5], v3 sc0
	v_cvt_f32_u32_e32 v3, v2
	v_sub_u32_e32 v5, 0, v2
	v_rcp_iflag_f32_e32 v3, v3
	s_nop 0
	v_mul_f32_e32 v3, 0x4f7ffffe, v3
	v_cvt_u32_f32_e32 v3, v3
	v_mul_lo_u32 v5, v5, v3
	v_mul_hi_u32 v5, v3, v5
	v_add_u32_e32 v3, v3, v5
	s_waitcnt vmcnt(0) lgkmcnt(0)
	v_mul_hi_u32 v3, v4, v3
	v_mul_lo_u32 v5, v3, v2
	v_sub_u32_e32 v5, v4, v5
	v_cmp_ge_u32_e32 vcc, v5, v2
	v_add_u32_e32 v6, 1, v3
	s_nop 0
	v_cndmask_b32_e32 v3, v3, v6, vcc
	v_sub_u32_e32 v6, v5, v2
	v_cndmask_b32_e32 v5, v5, v6, vcc
	v_cmp_ge_u32_e32 vcc, v5, v2
	v_add_u32_e32 v5, 1, v3
	v_add_u32_e32 v6, 1, v4
	v_cndmask_b32_e32 v3, v3, v5, vcc
	v_mad_u64_u32 v[4:5], s[0:1], v2, v3, v[2:3]
	v_cmp_ne_u32_e32 vcc, v6, v4
	s_and_saveexec_b64 s[0:1], vcc
	s_xor_b64 s[6:7], exec, s[0:1]
	s_cbranch_execz .LBB0_1275
	buffer_inv sc1
	v_mov_b32_e32 v0, s52
	v_add_co_u32_e32 v4, vcc, 0x3000, v0
	v_mov_b32_e32 v0, s53
	s_nop 0
	v_addc_co_u32_e32 v5, vcc, 0, v0, vcc
	flat_load_dword v0, v[4:5] offset:1280 sc1
	s_add_u32 s10, s52, 0x3500
	s_addc_u32 s11, s53, 0
	s_waitcnt vmcnt(0) lgkmcnt(0)
	v_cmp_eq_u32_e32 vcc, v0, v3
	s_and_saveexec_b64 s[8:9], vcc
	s_cbranch_execz .LBB0_1274
	s_mov_b32 s0, 1
	s_mov_b64 s[12:13], 0
	s_branch .LBB0_1266

; __device__ __forceinline__ unsigned xb_ld(unsigned* p)              { return __hip_atomic_load(p, __ATOMIC_RELAXED, __HIP_MEMORY_SCOPE_AGENT); }
; __device__ __forceinline__ unsigned xb_add(unsigned* p, unsigned v) { return __hip_atomic_fetch_add(p, v, __ATOMIC_RELAXED, __HIP_MEMORY_SCOPE_AGENT); }
; #define XB_SPIN(cond, bar) do { unsigned _sp = 0; while (cond) { __builtin_amdgcn_s_sleep(1); \
;     if ((++_sp & 255u) == 0u) { if (xb_ld(&(bar)[XB_TMO])) break; if (_sp > XB_SPIN_CAP) { atomicAdd(&(bar)[XB_TMO], 1u); break; } } } } while (0)
; __device__ __forceinline__ void xcd_barrier(const XcdBarrier& b) {
;     ...
;         if (old + 1u == (gen + 1u) * nloc) {
;             __builtin_amdgcn_fence(__ATOMIC_RELEASE, "agent");
;             asm volatile("s_waitcnt vmcnt(0)" ::: "memory");
;             const unsigned og = xb_add(&bar[XB_TOP], 1u);
;             const unsigned tg = og / nx;
;             if (og + 1u == (tg + 1u) * nx) xb_add(&bar[XB_TOPGEN], 1u);
;             else XB_SPIN(xb_ld(&bar[XB_TOPGEN]) == tg, bar);
;             __builtin_amdgcn_fence(__ATOMIC_ACQUIRE, "agent");
;             asm volatile("s_waitcnt vmcnt(0)" ::: "memory");
;         } else {
;             XB_SPIN(xb_ld(&bar[XB_TOPGEN]) == gen, bar);
;             __builtin_amdgcn_fence(__ATOMIC_ACQUIRE, "agent");
;             asm volatile("s_waitcnt vmcnt(0)" ::: "memory");
.LBB0_1274:
	s_or_b64 exec, exec, s[8:9]
	s_waitcnt vmcnt(0) lgkmcnt(0)
.LBB0_1275:
	s_andn2_saveexec_b64 s[0:1], s[6:7]
	s_cbranch_execz .LBB0_173
	v_mov_b32_e32 v2, s52
	v_add_co_u32_e32 v2, vcc, 0x3000, v2
	v_mov_b32_e32 v3, s53
	buffer_wbl2 sc1
	s_waitcnt vmcnt(0)
	v_addc_co_u32_e32 v3, vcc, 0, v3, vcc
	v_mov_b32_e32 v4, 1
	flat_atomic_add v2, v[2:3], v4 offset:1024 sc0
	v_cvt_f32_u32_e32 v3, v0
	v_sub_u32_e32 v4, 0, v0
	s_add_u32 s6, s52, 0x3500
	s_addc_u32 s7, s53, 0
	v_rcp_iflag_f32_e32 v3, v3
	s_mov_b64 s[10:11], -1
	v_mul_f32_e32 v3, 0x4f7ffffe, v3
	v_cvt_u32_f32_e32 v3, v3
	v_mul_lo_u32 v4, v4, v3
	v_mul_hi_u32 v4, v3, v4
	v_add_u32_e32 v3, v3, v4
	s_waitcnt vmcnt(0) lgkmcnt(0)
	v_mul_hi_u32 v3, v2, v3
	v_mul_lo_u32 v4, v3, v0
	v_sub_u32_e32 v4, v2, v4
	v_cmp_ge_u32_e32 vcc, v4, v0
	v_add_u32_e32 v5, 1, v3
	s_nop 0
	v_cndmask_b32_e32 v3, v3, v5, vcc
	v_sub_u32_e32 v5, v4, v0
	v_cndmask_b32_e32 v4, v4, v5, vcc
	v_cmp_ge_u32_e32 vcc, v4, v0
	v_add_u32_e32 v4, 1, v3
	v_add_u32_e32 v5, 1, v2
	v_cndmask_b32_e32 v4, v3, v4, vcc
	v_mad_u64_u32 v[2:3], s[0:1], v0, v4, v[0:1]
	v_cmp_ne_u32_e32 vcc, v5, v2
	v_mov_b64_e32 v[2:3], s[6:7]
	s_and_saveexec_b64 s[8:9], vcc
	s_cbranch_execz .LBB0_1288
	v_mov_b64_e32 v[2:3], s[6:7]
	flat_load_dword v0, v[2:3] sc1
	s_mov_b64 s[14:15], 0
	s_waitcnt vmcnt(0) lgkmcnt(0)
	v_cmp_eq_u32_e32 vcc, v0, v4
	s_and_saveexec_b64 s[12:13], vcc
	s_cbranch_execz .LBB0_1287
	s_add_u32 s10, s52, 0x200
	s_addc_u32 s11, s53, 0
	s_mov_b32 s0, 1
	s_branch .LBB0_1280
